# RWKV token staging rewritten by hand: per-token math without the compiler's serial reductions, the 16 wave sums of a block done at once by a permlane/DPP butterfly (383 instead of 768 instructions per
# speedup vs baseline: 1.0312x; 1.0312x over previous
.LBB0_564:
	v_mov_b32_e32 v78, v75
	v_mov_b32_e32 v76, v77
	s_and_b32 s3, s40, 1
	v_add_u32_e32 v28, s72, v76
	v_ashrrev_i32_e32 v29, 31, v28
	v_lshlrev_b64 v[10:11], 2, v[28:29]
	s_and_b32 s3, s40, 1
	s_mov_b32 s0, 0x17800
	s_mov_b32 s1, 0x1b800
	s_cmp_eq_u32 s3, 0
	s_cselect_b32 s41, 0x11800, s0
	s_cselect_b32 s16, 0x23800, s1
	v_lshlrev_b32_e32 v26, 3, v78
	v_mul_u32_u24_e32 v166, 0x880, v78
	v_lshl_add_u32 v166, v76, 2, v166
	v_lshlrev_b32_e32 v167, 11, v78
	v_lshl_add_u32 v167, v76, 2, v167
	v_add_u32_e32 v167, s41, v167
	v_mov_b32_e32 v140, 1.0
	v_sub_f32_e32 v169, v106, v44
	v_sub_f32_e32 v170, v35, v46
	v_sub_f32_e32 v171, v34, v48
	v_fma_f32 v169, v169, v115, v44
	v_fma_f32 v170, v170, v116, v46
	v_fma_f32 v171, v171, v119, v48
	v_add_f32_e32 v172, v50, v117
	v_add_f32_e32 v173, v107, v118
	v_mul_f32_e32 v172, 0xbfb8aa3b, v172
	v_mul_f32_e32 v173, 0xbfb8aa3b, v173
	v_exp_f32_e32 v172, v172
	v_exp_f32_e32 v173, v173
	ds_write_b32 v167, v171 offset:0
	v_add_f32_e32 v172, 1.0, v172
	v_add_f32_e32 v173, 1.0, v173
	v_rcp_f32_e32 v172, v172
	v_rcp_f32_e32 v173, v173
	v_mul_f32_e32 v124, v170, v120
	v_mul_f32_e32 v173, 0xbf1b4598, v173
	v_add_f32_e32 v174, -1.0, v172
	v_mul_f32_e32 v173, 0x3fb8aa3b, v173
	v_fma_f32 v174, v121, v174, 1.0
	v_exp_f32_e32 v173, v173
	v_mul_f32_e32 v174, v170, v174
	v_mul_f32_e32 v150, v124, v124
	v_mul_f32_e32 v175, v169, v174
	v_mul_f32_e32 v141, v140, v173
	v_mul_f32_e32 v158, v122, v175
	v_rcp_f32_e32 v176, v141
	v_mul_f32_e32 v169, v169, v141
	v_mul_f32_e32 v174, v174, v176
	v_mul_f32_e32 v132, v172, v176
	ds_write_b32 v166, v169 offset:17408
	ds_write_b32 v166, v174 offset:52224
	v_sub_f32_e32 v169, v44, v1
	v_sub_f32_e32 v170, v46, v45
	v_sub_f32_e32 v171, v48, v47
	v_fma_f32 v169, v169, v115, v1
	v_fma_f32 v170, v170, v116, v45
	v_fma_f32 v171, v171, v119, v47
	v_add_f32_e32 v172, v51, v117
	v_add_f32_e32 v173, v108, v118
	v_mul_f32_e32 v172, 0xbfb8aa3b, v172
	v_mul_f32_e32 v173, 0xbfb8aa3b, v173
	v_exp_f32_e32 v172, v172
	v_exp_f32_e32 v173, v173
	ds_write_b32 v167, v171 offset:256
	v_add_f32_e32 v172, 1.0, v172
	v_add_f32_e32 v173, 1.0, v173
	v_rcp_f32_e32 v172, v172
	v_rcp_f32_e32 v173, v173
	v_mul_f32_e32 v125, v170, v120
	v_mul_f32_e32 v173, 0xbf1b4598, v173
	v_add_f32_e32 v174, -1.0, v172
	v_mul_f32_e32 v173, 0x3fb8aa3b, v173
	v_fma_f32 v174, v121, v174, 1.0
	v_exp_f32_e32 v173, v173
	v_mul_f32_e32 v174, v170, v174
	v_mul_f32_e32 v152, v125, v125
	v_mul_f32_e32 v175, v169, v174
	v_mul_f32_e32 v142, v141, v173
	v_mul_f32_e32 v160, v122, v175
	v_rcp_f32_e32 v176, v142
	v_mul_f32_e32 v169, v169, v142
	v_mul_f32_e32 v174, v174, v176
	v_mul_f32_e32 v133, v172, v176
	ds_write_b32 v166, v169 offset:17680
	ds_write_b32 v166, v174 offset:52496
	v_sub_f32_e32 v169, v1, v52
	v_sub_f32_e32 v170, v45, v54
	v_sub_f32_e32 v171, v47, v56
	v_fma_f32 v169, v169, v115, v52
	v_fma_f32 v170, v170, v116, v54
	v_fma_f32 v171, v171, v119, v56
	v_add_f32_e32 v172, v58, v117
	v_add_f32_e32 v173, v109, v118
	v_mul_f32_e32 v172, 0xbfb8aa3b, v172
	v_mul_f32_e32 v173, 0xbfb8aa3b, v173
	v_exp_f32_e32 v172, v172
	v_exp_f32_e32 v173, v173
	ds_write_b32 v167, v171 offset:512
	v_add_f32_e32 v172, 1.0, v172
	v_add_f32_e32 v173, 1.0, v173
	v_rcp_f32_e32 v172, v172
	v_rcp_f32_e32 v173, v173
	v_mul_f32_e32 v126, v170, v120
	v_mul_f32_e32 v173, 0xbf1b4598, v173
	v_add_f32_e32 v174, -1.0, v172
	v_mul_f32_e32 v173, 0x3fb8aa3b, v173
	v_fma_f32 v174, v121, v174, 1.0
	v_exp_f32_e32 v173, v173
	v_mul_f32_e32 v174, v170, v174
	v_mul_f32_e32 v151, v126, v126
	v_mul_f32_e32 v175, v169, v174
	v_mul_f32_e32 v143, v142, v173
	v_mul_f32_e32 v159, v122, v175
	v_rcp_f32_e32 v176, v143
	v_mul_f32_e32 v169, v169, v143
	v_mul_f32_e32 v174, v174, v176
	v_mul_f32_e32 v134, v172, v176
	ds_write_b32 v166, v169 offset:17952
	ds_write_b32 v166, v174 offset:52768
	v_sub_f32_e32 v169, v52, v49
	v_sub_f32_e32 v170, v54, v53
	v_sub_f32_e32 v171, v56, v55
	v_fma_f32 v169, v169, v115, v49
	v_fma_f32 v170, v170, v116, v53
	v_fma_f32 v171, v171, v119, v55
	v_add_f32_e32 v172, v57, v117
	v_add_f32_e32 v173, v110, v118
	v_mul_f32_e32 v172, 0xbfb8aa3b, v172
	v_mul_f32_e32 v173, 0xbfb8aa3b, v173
	v_exp_f32_e32 v172, v172
	v_exp_f32_e32 v173, v173
	ds_write_b32 v167, v171 offset:768
	v_add_f32_e32 v172, 1.0, v172
	v_add_f32_e32 v173, 1.0, v173
	v_rcp_f32_e32 v172, v172
	v_rcp_f32_e32 v173, v173
	v_mul_f32_e32 v127, v170, v120
	v_mul_f32_e32 v173, 0xbf1b4598, v173
	v_add_f32_e32 v174, -1.0, v172
	v_mul_f32_e32 v173, 0x3fb8aa3b, v173
	v_fma_f32 v174, v121, v174, 1.0
	v_exp_f32_e32 v173, v173
	v_mul_f32_e32 v174, v170, v174
	v_mul_f32_e32 v153, v127, v127
	v_mul_f32_e32 v175, v169, v174
	v_mul_f32_e32 v144, v143, v173
	v_mul_f32_e32 v161, v122, v175
	v_rcp_f32_e32 v176, v144
	v_mul_f32_e32 v169, v169, v144
	v_mul_f32_e32 v174, v174, v176
	v_mul_f32_e32 v135, v172, v176
	ds_write_b32 v166, v169 offset:18224
	ds_write_b32 v166, v174 offset:53040
	v_sub_f32_e32 v169, v49, v60
	v_sub_f32_e32 v170, v53, v62
	v_sub_f32_e32 v171, v55, v64
	v_fma_f32 v169, v169, v115, v60
	v_fma_f32 v170, v170, v116, v62
	v_fma_f32 v171, v171, v119, v64
	v_add_f32_e32 v172, v66, v117
	v_add_f32_e32 v173, v111, v118
	v_mul_f32_e32 v172, 0xbfb8aa3b, v172
	v_mul_f32_e32 v173, 0xbfb8aa3b, v173
	v_exp_f32_e32 v172, v172
	v_exp_f32_e32 v173, v173
	ds_write_b32 v167, v171 offset:1024
	v_add_f32_e32 v172, 1.0, v172
	v_add_f32_e32 v173, 1.0, v173
	v_rcp_f32_e32 v172, v172
	v_rcp_f32_e32 v173, v173
	v_mul_f32_e32 v128, v170, v120
	v_mul_f32_e32 v173, 0xbf1b4598, v173
	v_add_f32_e32 v174, -1.0, v172
	v_mul_f32_e32 v173, 0x3fb8aa3b, v173
	v_fma_f32 v174, v121, v174, 1.0
	v_exp_f32_e32 v173, v173
	v_mul_f32_e32 v174, v170, v174
	v_mul_f32_e32 v154, v128, v128
	v_mul_f32_e32 v175, v169, v174
	v_mul_f32_e32 v145, v144, v173
	v_mul_f32_e32 v162, v122, v175
	v_rcp_f32_e32 v176, v145
	v_mul_f32_e32 v169, v169, v145
	v_mul_f32_e32 v174, v174, v176
	v_mul_f32_e32 v136, v172, v176
	ds_write_b32 v166, v169 offset:18496
	ds_write_b32 v166, v174 offset:53312
	v_sub_f32_e32 v169, v60, v59
	v_sub_f32_e32 v170, v62, v61
	v_sub_f32_e32 v171, v64, v63
	v_fma_f32 v169, v169, v115, v59
	v_fma_f32 v170, v170, v116, v61
	v_fma_f32 v171, v171, v119, v63
	v_add_f32_e32 v172, v65, v117
	v_add_f32_e32 v173, v112, v118
	v_mul_f32_e32 v172, 0xbfb8aa3b, v172
	v_mul_f32_e32 v173, 0xbfb8aa3b, v173
	v_exp_f32_e32 v172, v172
	v_exp_f32_e32 v173, v173
	ds_write_b32 v167, v171 offset:1280
	v_add_f32_e32 v172, 1.0, v172
	v_add_f32_e32 v173, 1.0, v173
	v_rcp_f32_e32 v172, v172
	v_rcp_f32_e32 v173, v173
	v_mul_f32_e32 v129, v170, v120
	v_mul_f32_e32 v173, 0xbf1b4598, v173
	v_add_f32_e32 v174, -1.0, v172
	v_mul_f32_e32 v173, 0x3fb8aa3b, v173
	v_fma_f32 v174, v121, v174, 1.0
	v_exp_f32_e32 v173, v173
	v_mul_f32_e32 v174, v170, v174
	v_mul_f32_e32 v156, v129, v129
	v_mul_f32_e32 v175, v169, v174
	v_mul_f32_e32 v146, v145, v173
	v_mul_f32_e32 v164, v122, v175
	v_rcp_f32_e32 v176, v146
	v_mul_f32_e32 v169, v169, v146
	v_mul_f32_e32 v174, v174, v176
	v_mul_f32_e32 v137, v172, v176
	ds_write_b32 v166, v169 offset:18768
	ds_write_b32 v166, v174 offset:53584
	v_sub_f32_e32 v169, v59, v67
	v_sub_f32_e32 v170, v61, v69
	v_sub_f32_e32 v171, v63, v71
	v_fma_f32 v169, v169, v115, v67
	v_fma_f32 v170, v170, v116, v69
	v_fma_f32 v171, v171, v119, v71
	v_add_f32_e32 v172, v74, v117
	v_add_f32_e32 v173, v113, v118
	v_mul_f32_e32 v172, 0xbfb8aa3b, v172
	v_mul_f32_e32 v173, 0xbfb8aa3b, v173
	v_exp_f32_e32 v172, v172
	v_exp_f32_e32 v173, v173
	ds_write_b32 v167, v171 offset:1536
	v_add_f32_e32 v172, 1.0, v172
	v_add_f32_e32 v173, 1.0, v173
	v_rcp_f32_e32 v172, v172
	v_rcp_f32_e32 v173, v173
	v_mul_f32_e32 v130, v170, v120
	v_mul_f32_e32 v173, 0xbf1b4598, v173
	v_add_f32_e32 v174, -1.0, v172
	v_mul_f32_e32 v173, 0x3fb8aa3b, v173
	v_fma_f32 v174, v121, v174, 1.0
	v_exp_f32_e32 v173, v173
	v_mul_f32_e32 v174, v170, v174
	v_mul_f32_e32 v155, v130, v130
	v_mul_f32_e32 v175, v169, v174
	v_mul_f32_e32 v147, v146, v173
	v_mul_f32_e32 v163, v122, v175
	v_rcp_f32_e32 v176, v147
	v_mul_f32_e32 v169, v169, v147
	v_mul_f32_e32 v174, v174, v176
	v_mul_f32_e32 v138, v172, v176
	ds_write_b32 v166, v169 offset:19040
	ds_write_b32 v166, v174 offset:53856
	v_sub_f32_e32 v169, v67, v68
	v_sub_f32_e32 v170, v69, v70
	v_sub_f32_e32 v171, v71, v72
	v_fma_f32 v169, v169, v115, v68
	v_fma_f32 v170, v170, v116, v70
	v_fma_f32 v171, v171, v119, v72
	v_add_f32_e32 v172, v73, v117
	v_add_f32_e32 v173, v114, v118
	v_mul_f32_e32 v172, 0xbfb8aa3b, v172
	v_mul_f32_e32 v173, 0xbfb8aa3b, v173
	v_exp_f32_e32 v172, v172
	v_exp_f32_e32 v173, v173
	ds_write_b32 v167, v171 offset:1792
	v_add_f32_e32 v172, 1.0, v172
	v_add_f32_e32 v173, 1.0, v173
	v_rcp_f32_e32 v172, v172
	v_rcp_f32_e32 v173, v173
	v_mul_f32_e32 v131, v170, v120
	v_mul_f32_e32 v173, 0xbf1b4598, v173
	v_add_f32_e32 v174, -1.0, v172
	v_mul_f32_e32 v173, 0x3fb8aa3b, v173
	v_fma_f32 v174, v121, v174, 1.0
	v_exp_f32_e32 v173, v173
	v_mul_f32_e32 v174, v170, v174
	v_mul_f32_e32 v157, v131, v131
	v_mul_f32_e32 v175, v169, v174
	v_mul_f32_e32 v148, v147, v173
	v_mul_f32_e32 v165, v122, v175
	v_rcp_f32_e32 v176, v148
	v_mul_f32_e32 v169, v169, v148
	v_mul_f32_e32 v174, v174, v176
	v_mul_f32_e32 v139, v172, v176
	ds_write_b32 v166, v169 offset:19312
	ds_write_b32 v166, v174 offset:54128
	v_permlane32_swap_b32_e32 v150, v151
	v_permlane32_swap_b32_e32 v152, v153
	v_permlane32_swap_b32_e32 v154, v155
	v_permlane32_swap_b32_e32 v156, v157
	v_permlane32_swap_b32_e32 v158, v159
	v_permlane32_swap_b32_e32 v160, v161
	v_permlane32_swap_b32_e32 v162, v163
	v_permlane32_swap_b32_e32 v164, v165
	v_add_f32_e32 v182, v150, v151
	v_add_f32_e32 v183, v152, v153
	v_add_f32_e32 v184, v154, v155
	v_add_f32_e32 v185, v156, v157
	v_add_f32_e32 v186, v158, v159
	v_add_f32_e32 v187, v160, v161
	v_add_f32_e32 v188, v162, v163
	v_add_f32_e32 v189, v164, v165
	v_permlane16_swap_b32_e32 v182, v183
	v_permlane16_swap_b32_e32 v184, v185
	v_permlane16_swap_b32_e32 v186, v187
	v_permlane16_swap_b32_e32 v188, v189
	v_add_f32_e32 v190, v182, v183
	v_add_f32_e32 v191, v184, v185
	v_add_f32_e32 v192, v186, v187
	v_add_f32_e32 v193, v188, v189
	v_add_f32_dpp v194, v190, v190 row_mirror row_mask:0xf bank_mask:0x3
	v_add_f32_dpp v194, v191, v191 row_mirror row_mask:0xf bank_mask:0xc
	v_add_f32_dpp v195, v192, v192 row_mirror row_mask:0xf bank_mask:0x3
	v_add_f32_dpp v195, v193, v193 row_mirror row_mask:0xf bank_mask:0xc
	v_add_f32_dpp v196, v194, v194 row_half_mirror row_mask:0xf bank_mask:0x5
	s_nop 0
	v_add_f32_dpp v196, v195, v195 row_half_mirror row_mask:0xf bank_mask:0xa
	s_nop 1
	v_add_f32_dpp v196, v196, v196 quad_perm:[1,0,3,2] row_mask:0xf bank_mask:0xf
	s_nop 1
	v_add_f32_dpp v196, v196, v196 quad_perm:[2,3,0,1] row_mask:0xf bank_mask:0xf
	v_add_f32_e32 v197, 0x2b8cbccc, v196
	v_lshrrev_b32_e32 v198, 4, v76
	v_rsq_f32_e32 v197, v197
	v_bfe_u32 v168, v76, 3, 1
	v_lshl_add_u32 v198, v168, 2, v198
	v_add_u32_e32 v198, v198, v26
	v_lshl_add_u32 v198, v198, 2, s16
	s_mov_b32 s4, 0x10101010
	s_mov_b32 s5, 0x10101010
	s_mov_b64 exec, s[4:5]
	ds_write_b32 v198, v196
	s_mov_b64 exec, -1
	v_readlane_b32 s0, v197, 0
	v_readlane_b32 s1, v197, 16
	v_readlane_b32 s3, v197, 32
	v_readlane_b32 s4, v197, 48
	v_mul_f32_e32 v124, s0, v124
	v_mul_f32_e32 v125, s1, v125
	v_mul_f32_e32 v126, s3, v126
	v_mul_f32_e32 v127, s4, v127
	v_mul_f32_e64 v169, v124, -v140
	v_mul_f32_e32 v132, v124, v132
	v_mul_f32_e64 v170, v125, -v141
	v_mul_f32_e32 v133, v125, v133
	v_mul_f32_e64 v171, v126, -v142
	v_mul_f32_e32 v134, v126, v134
	v_mul_f32_e64 v172, v127, -v143
	v_mul_f32_e32 v135, v127, v135
	ds_write_b32 v166, v169 offset:0
	ds_write_b32 v166, v132 offset:34816
	ds_write_b32 v166, v170 offset:272
	ds_write_b32 v166, v133 offset:35088
	ds_write_b32 v166, v171 offset:544
	ds_write_b32 v166, v134 offset:35360
	ds_write_b32 v166, v172 offset:816
	ds_write_b32 v166, v135 offset:35632
	v_readlane_b32 s0, v197, 8
	v_readlane_b32 s1, v197, 24
	v_readlane_b32 s3, v197, 40
	v_readlane_b32 s4, v197, 56
	v_mul_f32_e32 v128, s0, v128
	v_mul_f32_e32 v129, s1, v129
	v_mul_f32_e32 v130, s3, v130
	v_mul_f32_e32 v131, s4, v131
	v_mul_f32_e64 v169, v128, -v144
	v_mul_f32_e32 v136, v128, v136
	v_mul_f32_e64 v170, v129, -v145
	v_mul_f32_e32 v137, v129, v137
	v_mul_f32_e64 v171, v130, -v146
	v_mul_f32_e32 v138, v130, v138
	v_mul_f32_e64 v172, v131, -v147
	v_mul_f32_e32 v139, v131, v139
	ds_write_b32 v166, v169 offset:1088
	ds_write_b32 v166, v136 offset:35904
	ds_write_b32 v166, v170 offset:1360
	ds_write_b32 v166, v137 offset:36176
	ds_write_b32 v166, v171 offset:1632
	ds_write_b32 v166, v138 offset:36448
	ds_write_b32 v166, v172 offset:1904
	ds_write_b32 v166, v139 offset:36720
	v_lshlrev_b32_e32 v168, 8, v78
	v_lshl_add_u32 v168, v76, 2, v168
	v_add_u32_e32 v168, 0x11000, v168
	ds_write_b32 v168, v148
	v_and_b32_e32 v124, 15, v76
	v_lshrrev_b32_e32 v125, 4, v76
	v_and_b32_e32 v132, 7, v124
	v_add_u32_e32 v126, v26, v132
	v_mul_u32_u24_e32 v126, 0x110, v126
	v_lshl_add_u32 v126, v125, 4, v126
	v_and_b32_e32 v127, 8, v124
	v_mul_u32_u24_e32 v127, 0x880, v127
	v_add_u32_e32 v128, v126, v127
	v_add_u32_e32 v129, 0x8800, v128
	ds_read_b128 v[136:139], v128 offset:0
	ds_read_b128 v[152:155], v129 offset:0
	ds_read_b128 v[140:143], v128 offset:64
	ds_read_b128 v[156:159], v129 offset:64
	ds_read_b128 v[144:147], v128 offset:128
	ds_read_b128 v[160:163], v129 offset:128
	ds_read_b128 v[148:151], v128 offset:192
	ds_read_b128 v[164:167], v129 offset:192
	v_lshrrev_b32_e32 v126, 1, v125
	v_lshrrev_b32_e32 v127, 3, v124
	v_lshl_add_u32 v127, v126, 1, v127
	v_lshlrev_b32_e32 v130, 8, v127
	v_lshl_add_u32 v130, v26, 7, v130
	v_and_b32_e32 v127, 1, v125
	v_lshl_add_u32 v130, v127, 7, v130
	v_lshl_add_u32 v130, v132, 2, v130
	v_add_u32_e32 v130, 0x15800, v130
	v_sub_u32_e32 v131, 1, v126
	v_add_u32_e32 v131, v131, v132
	v_lshlrev_b32_e32 v127, 2, v127
	v_sub_u32_e32 v131, v131, v127
	v_max_i32_e32 v131, 0, v131
	v_cmp_ge_u32_e64 s[0:1], 1, v131
	v_cmp_ge_u32_e64 s[4:5], 2, v131
	v_cmp_ge_u32_e64 s[6:7], 3, v131
	v_cmp_ge_u32_e32 vcc, 0, v131
	s_waitcnt lgkmcnt(0)
	v_mfma_f32_16x16x4_f32 v[36:39], v136, v152, 0
	v_mfma_f32_16x16x4_f32 v[40:43], v137, v153, 0
	v_mfma_f32_16x16x4_f32 v[36:39], v138, v154, v[36:39]
	v_mfma_f32_16x16x4_f32 v[40:43], v139, v155, v[40:43]
	v_mfma_f32_16x16x4_f32 v[36:39], v140, v156, v[36:39]
	v_mfma_f32_16x16x4_f32 v[40:43], v141, v157, v[40:43]
	v_mfma_f32_16x16x4_f32 v[36:39], v142, v158, v[36:39]
	v_mfma_f32_16x16x4_f32 v[40:43], v143, v159, v[40:43]
	v_mfma_f32_16x16x4_f32 v[36:39], v144, v160, v[36:39]
	v_mfma_f32_16x16x4_f32 v[40:43], v145, v161, v[40:43]
	v_mfma_f32_16x16x4_f32 v[36:39], v146, v162, v[36:39]
	v_mfma_f32_16x16x4_f32 v[40:43], v147, v163, v[40:43]
	v_mfma_f32_16x16x4_f32 v[36:39], v148, v164, v[36:39]
	v_mfma_f32_16x16x4_f32 v[40:43], v149, v165, v[40:43]
	v_mfma_f32_16x16x4_f32 v[36:39], v150, v166, v[36:39]
	v_mfma_f32_16x16x4_f32 v[40:43], v151, v167, v[40:43]
	s_nop 7
	s_nop 2
	v_pk_add_f32 v[36:37], v[36:37], v[40:41]
	v_pk_add_f32 v[38:39], v[38:39], v[42:43]
	v_cndmask_b32_e32 v36, 0, v36, vcc
	v_cndmask_b32_e64 v37, 0, v37, s[0:1]
	v_cndmask_b32_e64 v38, 0, v38, s[4:5]
	v_cndmask_b32_e64 v39, 0, v39, s[6:7]
	ds_write_b32 v130, v36 offset:0
	ds_write_b32 v130, v37 offset:32
	ds_write_b32 v130, v38 offset:64
	ds_write_b32 v130, v39 offset:96
	v_mov_b32_e32 v168, v132
	v_lshlrev_b32_e32 v169, 7, v26
	v_add_u32_e32 v169, 0x15800, v169
	v_lshl_add_u32 v172, v125, 6, v169
	v_lshl_add_u32 v170, v132, 2, v169
	v_lshl_add_u32 v173, v132, 2, v172
	v_mov_b32_e32 v171, 1.0
	ds_read_b128 v[124:127], v169 offset:32
	ds_read_b128 v[128:131], v169 offset:64
	ds_read_b128 v[132:135], v169 offset:96
	ds_read_b128 v[136:139], v169 offset:128
	ds_read_b128 v[144:147], v169 offset:160
	ds_read_b128 v[148:151], v169 offset:176
	ds_read_b128 v[152:155], v169 offset:192
	ds_read_b128 v[156:159], v169 offset:208
	ds_read_b128 v[160:163], v169 offset:224
	ds_read_b128 v[164:167], v169 offset:240
	ds_read_b128 v[182:185], v172 offset:512
	ds_read_b128 v[186:189], v172 offset:528
	ds_read_b128 v[190:193], v172 offset:544
	ds_read_b128 v[194:197], v172 offset:560
	v_cmp_eq_u32_e32 vcc, 0, v168
	v_cndmask_b32_e32 v36, 0, v171, vcc
	v_cmp_eq_u32_e32 vcc, 1, v168
	v_cndmask_b32_e32 v37, 0, v171, vcc
	v_cmp_eq_u32_e32 vcc, 2, v168
	v_cndmask_b32_e32 v38, 0, v171, vcc
	v_cmp_eq_u32_e32 vcc, 3, v168
	v_cndmask_b32_e32 v39, 0, v171, vcc
	v_cmp_eq_u32_e32 vcc, 4, v168
	v_cndmask_b32_e32 v40, 0, v171, vcc
	v_cmp_eq_u32_e32 vcc, 5, v168
	v_cndmask_b32_e32 v41, 0, v171, vcc
	v_cmp_eq_u32_e32 vcc, 6, v168
	v_cndmask_b32_e32 v42, 0, v171, vcc
	v_cmp_eq_u32_e32 vcc, 7, v168
	v_cndmask_b32_e32 v43, 0, v171, vcc
	s_waitcnt lgkmcnt(0)
	v_fmac_f32_e32 v37, v124, v36
	v_fmac_f32_e32 v38, v128, v36
	v_fmac_f32_e32 v39, v132, v36
	v_fmac_f32_e32 v40, v136, v36
	v_fmac_f32_e32 v41, v144, v36
	v_fmac_f32_e32 v42, v152, v36
	v_fmac_f32_e32 v43, v160, v36
	v_fmac_f32_e32 v38, v129, v37
	v_fmac_f32_e32 v39, v133, v37
	v_fmac_f32_e32 v40, v137, v37
	v_fmac_f32_e32 v41, v145, v37
	v_fmac_f32_e32 v42, v153, v37
	v_fmac_f32_e32 v43, v161, v37
	v_fmac_f32_e32 v39, v134, v38
	v_fmac_f32_e32 v40, v138, v38
	v_fmac_f32_e32 v41, v146, v38
	v_fmac_f32_e32 v42, v154, v38
	v_fmac_f32_e32 v43, v162, v38
	v_fmac_f32_e32 v40, v139, v39
	v_fmac_f32_e32 v41, v147, v39
	v_fmac_f32_e32 v42, v155, v39
	v_fmac_f32_e32 v43, v163, v39
	v_fmac_f32_e32 v41, v148, v40
	v_fmac_f32_e32 v42, v156, v40
	v_fmac_f32_e32 v43, v164, v40
	v_fmac_f32_e32 v42, v157, v41
	v_fmac_f32_e32 v43, v165, v41
	v_fmac_f32_e32 v43, v166, v42
	v_mul_f32_e32 v44, v182, v36
	v_fmac_f32_e32 v44, v183, v37
	v_fmac_f32_e32 v44, v184, v38
	v_fmac_f32_e32 v44, v185, v39
	v_fmac_f32_e32 v44, v186, v40
	v_fmac_f32_e32 v44, v187, v41
	v_fmac_f32_e32 v44, v188, v42
	v_fmac_f32_e32 v44, v189, v43
	v_mul_f32_e32 v45, v190, v36
	v_fmac_f32_e32 v45, v191, v37
	v_fmac_f32_e32 v45, v192, v38
	v_fmac_f32_e32 v45, v193, v39
	v_fmac_f32_e32 v45, v194, v40
	v_fmac_f32_e32 v45, v195, v41
	v_fmac_f32_e32 v45, v196, v42
	v_fmac_f32_e32 v45, v197, v43
	ds_write_b32 v170, v36 offset:0
	ds_write_b32 v170, v37 offset:32
	ds_write_b32 v170, v38 offset:64
	ds_write_b32 v170, v39 offset:96
	ds_write_b32 v170, v40 offset:128
	ds_write_b32 v170, v41 offset:160
	ds_write_b32 v170, v42 offset:192
	ds_write_b32 v170, v43 offset:224
	ds_write_b32 v173, v44 offset:512
	ds_write_b32 v173, v45 offset:544
	s_lshl_b32 s17, s40, 6
	s_cmp_lg_u32 s40, 31
	s_waitcnt lgkmcnt(0)
	s_barrier
	s_cbranch_scc0 .LBB0_586
	v_readfirstlane_b32 s0, v180
	s_nop 1
	s_cmpk_ge_u32 s0, 0x100
	s_cbranch_scc1 .LBB0_586
	s_add_i32 s3, s17, 64
	s_add_u32 s0, s80, s3
	s_addc_u32 s1, s81, 0
	v_ashrrev_i32_e32 v27, 31, v26
	v_lshl_add_u64 v[4:5], s[0:1], 0, v[26:27]
	v_mad_u64_u32 v[2:3], s[0:1], v4, s83, 0
	v_mad_i32_i24 v3, v5, s83, v3
	v_add_u32_e32 v1, s3, v26
	v_mov_b32_e32 v95, v94
	v_lshl_add_u64 v[2:3], s[46:47], 0, v[2:3]
	v_cmp_lt_i32_e32 vcc, 0, v1
	v_mov_b32_e32 v106, 0
	v_lshl_add_u64 v[2:3], v[28:29], 1, v[2:3]
	v_mov_b64_e32 v[34:35], v[94:95]
	s_and_saveexec_b64 s[0:1], vcc
	s_cbranch_execz .LBB0_585
	global_load_ushort v52, v[2:3], off offset:-3072
	global_load_ushort v53, v[2:3], off offset:-2048
	global_load_ushort v54, v[2:3], off offset:-1024
